# v16 + per-unit accumulator zeroing via 64 v_mov_b64 instead of 128 v_mov_b32 in 14 GEMM unit loops
# speedup vs baseline: 1.0019x; 1.0004x over previous
.LBB0_401:
	s_add_u32 s9, s60, 0x100
	s_addc_u32 s10, s61, 0
	s_add_u32 s60, s62, 0x100080
	v_mov_b32_e32 v2, 0
	s_addc_u32 s61, s63, 0
	s_mov_b32 s39, -2
	v_mov_b32_e32 v3, 0
	v_mov_b64_e32 v[4:5], v[2:3]
	v_mov_b64_e32 v[6:7], v[2:3]
	v_mov_b64_e32 v[8:9], v[2:3]
	v_mov_b64_e32 v[10:11], v[2:3]
	v_mov_b64_e32 v[12:13], v[2:3]
	v_mov_b64_e32 v[14:15], v[2:3]
	v_mov_b64_e32 v[16:17], v[2:3]
	v_mov_b64_e32 v[18:19], v[2:3]
	v_mov_b64_e32 v[20:21], v[2:3]
	v_mov_b64_e32 v[22:23], v[2:3]
	v_mov_b64_e32 v[24:25], v[2:3]
	v_mov_b64_e32 v[26:27], v[2:3]
	v_mov_b64_e32 v[28:29], v[2:3]
	v_mov_b64_e32 v[30:31], v[2:3]
	v_mov_b64_e32 v[32:33], v[2:3]
	v_mov_b64_e32 v[34:35], v[2:3]
	v_mov_b64_e32 v[36:37], v[2:3]
	v_mov_b64_e32 v[38:39], v[2:3]
	v_mov_b64_e32 v[40:41], v[2:3]
	v_mov_b64_e32 v[42:43], v[2:3]
	v_mov_b64_e32 v[44:45], v[2:3]
	v_mov_b64_e32 v[46:47], v[2:3]
	v_mov_b64_e32 v[48:49], v[2:3]
	v_mov_b64_e32 v[50:51], v[2:3]
	v_mov_b64_e32 v[52:53], v[2:3]
	v_mov_b64_e32 v[54:55], v[2:3]
	v_mov_b64_e32 v[56:57], v[2:3]
	v_mov_b64_e32 v[58:59], v[2:3]
	v_mov_b64_e32 v[60:61], v[2:3]
	v_mov_b64_e32 v[62:63], v[2:3]
	v_mov_b64_e32 v[64:65], v[2:3]
	v_mov_b64_e32 v[66:67], v[2:3]
	v_mov_b64_e32 v[68:69], v[2:3]
	v_mov_b64_e32 v[70:71], v[2:3]
	v_mov_b64_e32 v[72:73], v[2:3]
	v_mov_b64_e32 v[74:75], v[2:3]
	v_mov_b64_e32 v[76:77], v[2:3]
	v_mov_b64_e32 v[78:79], v[2:3]
	v_mov_b64_e32 v[80:81], v[2:3]
	v_mov_b64_e32 v[82:83], v[2:3]
	v_mov_b64_e32 v[84:85], v[2:3]
	v_mov_b64_e32 v[86:87], v[2:3]
	v_mov_b64_e32 v[88:89], v[2:3]
	v_mov_b64_e32 v[90:91], v[2:3]
	v_mov_b64_e32 v[92:93], v[2:3]
	v_mov_b64_e32 v[94:95], v[2:3]
	v_mov_b64_e32 v[96:97], v[2:3]
	v_mov_b64_e32 v[98:99], v[2:3]
	v_mov_b64_e32 v[100:101], v[2:3]
	v_mov_b64_e32 v[102:103], v[2:3]
	v_mov_b64_e32 v[104:105], v[2:3]
	v_mov_b64_e32 v[106:107], v[2:3]
	v_mov_b64_e32 v[108:109], v[2:3]
	v_mov_b64_e32 v[110:111], v[2:3]
	v_mov_b64_e32 v[112:113], v[2:3]
	v_mov_b64_e32 v[114:115], v[2:3]
	v_mov_b64_e32 v[116:117], v[2:3]
	v_mov_b64_e32 v[118:119], v[2:3]
	v_mov_b64_e32 v[120:121], v[2:3]
	v_mov_b64_e32 v[122:123], v[2:3]
	v_mov_b64_e32 v[124:125], v[2:3]
	v_mov_b64_e32 v[126:127], v[2:3]
	v_mov_b64_e32 v[128:129], v[2:3]
	s_waitcnt vmcnt(0)

.LBB0_696:
	s_ashr_i32 s29, s28, 31
	s_lshl_b64 s[30:31], s[28:29], 20
	s_add_u32 s30, s3, s30
	s_addc_u32 s31, s25, s31
	s_and_b64 s[34:35], s[6:7], exec
	s_cselect_b32 s29, s31, s39
	s_cselect_b32 s68, s30, s38
	s_ashr_i32 s27, s26, 31
	s_lshl_b64 s[34:35], s[26:27], 20
	s_add_u32 s34, s42, s34
	s_addc_u32 s35, s43, s35
	s_and_b64 s[40:41], s[6:7], exec
	s_cselect_b32 s27, s35, s37
	s_cselect_b32 s69, s34, s36
	s_add_u32 s70, s36, 0x100
	s_addc_u32 s71, s37, 0
	s_add_u32 s36, s38, 0x80080
	v_mov_b32_e32 v10, 0
	s_addc_u32 s37, s39, 0
	s_mov_b32 s72, -2
	v_mov_b32_e32 v11, 0
	v_mov_b64_e32 v[12:13], v[10:11]
	v_mov_b64_e32 v[14:15], v[10:11]
	v_mov_b64_e32 v[16:17], v[10:11]
	v_mov_b64_e32 v[18:19], v[10:11]
	v_mov_b64_e32 v[20:21], v[10:11]
	v_mov_b64_e32 v[22:23], v[10:11]
	v_mov_b64_e32 v[24:25], v[10:11]
	v_mov_b64_e32 v[26:27], v[10:11]
	v_mov_b64_e32 v[28:29], v[10:11]
	v_mov_b64_e32 v[30:31], v[10:11]
	v_mov_b64_e32 v[32:33], v[10:11]
	v_mov_b64_e32 v[34:35], v[10:11]
	v_mov_b64_e32 v[36:37], v[10:11]
	v_mov_b64_e32 v[38:39], v[10:11]
	v_mov_b64_e32 v[40:41], v[10:11]
	v_mov_b64_e32 v[42:43], v[10:11]
	v_mov_b64_e32 v[44:45], v[10:11]
	v_mov_b64_e32 v[46:47], v[10:11]
	v_mov_b64_e32 v[48:49], v[10:11]
	v_mov_b64_e32 v[50:51], v[10:11]
	v_mov_b64_e32 v[52:53], v[10:11]
	v_mov_b64_e32 v[54:55], v[10:11]
	v_mov_b64_e32 v[56:57], v[10:11]
	v_mov_b64_e32 v[58:59], v[10:11]
	v_mov_b64_e32 v[60:61], v[10:11]
	v_mov_b64_e32 v[62:63], v[10:11]
	v_mov_b64_e32 v[64:65], v[10:11]
	v_mov_b64_e32 v[66:67], v[10:11]
	v_mov_b64_e32 v[68:69], v[10:11]
	v_mov_b64_e32 v[70:71], v[10:11]
	v_mov_b64_e32 v[72:73], v[10:11]
	v_mov_b64_e32 v[74:75], v[10:11]
	v_mov_b64_e32 v[76:77], v[10:11]
	v_mov_b64_e32 v[78:79], v[10:11]
	v_mov_b64_e32 v[80:81], v[10:11]
	v_mov_b64_e32 v[82:83], v[10:11]
	v_mov_b64_e32 v[84:85], v[10:11]
	v_mov_b64_e32 v[86:87], v[10:11]
	v_mov_b64_e32 v[88:89], v[10:11]
	v_mov_b64_e32 v[90:91], v[10:11]
	v_mov_b64_e32 v[92:93], v[10:11]
	v_mov_b64_e32 v[94:95], v[10:11]
	v_mov_b64_e32 v[96:97], v[10:11]
	v_mov_b64_e32 v[98:99], v[10:11]
	v_mov_b64_e32 v[100:101], v[10:11]
	v_mov_b64_e32 v[102:103], v[10:11]
	v_mov_b64_e32 v[104:105], v[10:11]
	v_mov_b64_e32 v[106:107], v[10:11]
	v_mov_b64_e32 v[108:109], v[10:11]
	v_mov_b64_e32 v[110:111], v[10:11]
	v_mov_b64_e32 v[112:113], v[10:11]
	v_mov_b64_e32 v[114:115], v[10:11]
	v_mov_b64_e32 v[116:117], v[10:11]
	v_mov_b64_e32 v[118:119], v[10:11]
	v_mov_b64_e32 v[120:121], v[10:11]
	v_mov_b64_e32 v[122:123], v[10:11]
	v_mov_b64_e32 v[124:125], v[10:11]
	v_mov_b64_e32 v[126:127], v[10:11]
	v_mov_b64_e32 v[128:129], v[10:11]
	v_mov_b64_e32 v[130:131], v[10:11]
	v_mov_b64_e32 v[132:133], v[10:11]
	v_mov_b64_e32 v[134:135], v[10:11]
	v_mov_b64_e32 v[136:137], v[10:11]

.LBB0_789:
	s_add_u32 s75, s24, 0x100
	s_addc_u32 s76, s25, 0
	s_add_u32 s24, s26, 0x100080
	v_mov_b32_e32 v2, 0
	s_addc_u32 s25, s27, 0
	s_mov_b32 s77, -2
	v_mov_b32_e32 v3, 0
	v_mov_b64_e32 v[4:5], v[2:3]
	v_mov_b64_e32 v[6:7], v[2:3]
	v_mov_b64_e32 v[8:9], v[2:3]
	v_mov_b64_e32 v[10:11], v[2:3]
	v_mov_b64_e32 v[12:13], v[2:3]
	v_mov_b64_e32 v[14:15], v[2:3]
	v_mov_b64_e32 v[16:17], v[2:3]
	v_mov_b64_e32 v[18:19], v[2:3]
	v_mov_b64_e32 v[20:21], v[2:3]
	v_mov_b64_e32 v[22:23], v[2:3]
	v_mov_b64_e32 v[24:25], v[2:3]
	v_mov_b64_e32 v[26:27], v[2:3]
	v_mov_b64_e32 v[28:29], v[2:3]
	v_mov_b64_e32 v[30:31], v[2:3]
	v_mov_b64_e32 v[32:33], v[2:3]
	v_mov_b64_e32 v[34:35], v[2:3]
	v_mov_b64_e32 v[36:37], v[2:3]
	v_mov_b64_e32 v[38:39], v[2:3]
	v_mov_b64_e32 v[40:41], v[2:3]
	v_mov_b64_e32 v[42:43], v[2:3]
	v_mov_b64_e32 v[44:45], v[2:3]
	v_mov_b64_e32 v[46:47], v[2:3]
	v_mov_b64_e32 v[48:49], v[2:3]
	v_mov_b64_e32 v[50:51], v[2:3]
	v_mov_b64_e32 v[52:53], v[2:3]
	v_mov_b64_e32 v[54:55], v[2:3]
	v_mov_b64_e32 v[56:57], v[2:3]
	v_mov_b64_e32 v[58:59], v[2:3]
	v_mov_b64_e32 v[60:61], v[2:3]
	v_mov_b64_e32 v[62:63], v[2:3]
	v_mov_b64_e32 v[64:65], v[2:3]
	v_mov_b64_e32 v[66:67], v[2:3]
	v_mov_b64_e32 v[68:69], v[2:3]
	v_mov_b64_e32 v[70:71], v[2:3]
	v_mov_b64_e32 v[72:73], v[2:3]
	v_mov_b64_e32 v[74:75], v[2:3]
	v_mov_b64_e32 v[76:77], v[2:3]
	v_mov_b64_e32 v[78:79], v[2:3]
	v_mov_b64_e32 v[80:81], v[2:3]
	v_mov_b64_e32 v[82:83], v[2:3]
	v_mov_b64_e32 v[84:85], v[2:3]
	v_mov_b64_e32 v[86:87], v[2:3]
	v_mov_b64_e32 v[88:89], v[2:3]
	v_mov_b64_e32 v[90:91], v[2:3]
	v_mov_b64_e32 v[92:93], v[2:3]
	v_mov_b64_e32 v[94:95], v[2:3]
	v_mov_b64_e32 v[96:97], v[2:3]
	v_mov_b64_e32 v[98:99], v[2:3]
	v_mov_b64_e32 v[100:101], v[2:3]
	v_mov_b64_e32 v[102:103], v[2:3]
	v_mov_b64_e32 v[104:105], v[2:3]
	v_mov_b64_e32 v[106:107], v[2:3]
	v_mov_b64_e32 v[108:109], v[2:3]
	v_mov_b64_e32 v[110:111], v[2:3]
	v_mov_b64_e32 v[112:113], v[2:3]
	v_mov_b64_e32 v[114:115], v[2:3]
	v_mov_b64_e32 v[116:117], v[2:3]
	v_mov_b64_e32 v[118:119], v[2:3]
	v_mov_b64_e32 v[120:121], v[2:3]
	v_mov_b64_e32 v[122:123], v[2:3]
	v_mov_b64_e32 v[124:125], v[2:3]
	v_mov_b64_e32 v[126:127], v[2:3]
	v_mov_b64_e32 v[128:129], v[2:3]

.LBB0_1280:
	s_ashr_i32 s27, s26, 31
	s_lshl_b64 s[28:29], s[26:27], 21
	s_add_u32 s28, s3, s28
	s_addc_u32 s29, s44, s29
	s_and_b64 s[30:31], s[8:9], exec
	s_cselect_b32 s27, s29, s41
	s_cselect_b32 s35, s28, s40
	s_ashr_i32 s15, s14, 31
	s_lshl_b64 s[30:31], s[14:15], 21
	s_add_u32 s30, s45, s30
	s_addc_u32 s31, s46, s31
	s_and_b64 s[42:43], s[8:9], exec
	s_cselect_b32 s15, s31, s39
	s_cselect_b32 s37, s30, s38
	s_add_u32 s70, s38, 0x100
	s_addc_u32 s71, s39, 0
	s_add_u32 s38, s40, 0x100080
	v_mov_b32_e32 v2, 0
	s_addc_u32 s39, s41, 0
	s_mov_b32 s72, -2
	s_waitcnt lgkmcnt(0)
	v_mov_b32_e32 v3, 0
	v_mov_b64_e32 v[4:5], v[2:3]
	v_mov_b64_e32 v[6:7], v[2:3]
	v_mov_b64_e32 v[8:9], v[2:3]
	v_mov_b64_e32 v[10:11], v[2:3]
	v_mov_b64_e32 v[12:13], v[2:3]
	v_mov_b64_e32 v[14:15], v[2:3]
	v_mov_b64_e32 v[16:17], v[2:3]
	v_mov_b64_e32 v[18:19], v[2:3]
	v_mov_b64_e32 v[20:21], v[2:3]
	v_mov_b64_e32 v[22:23], v[2:3]
	v_mov_b64_e32 v[24:25], v[2:3]
	v_mov_b64_e32 v[26:27], v[2:3]
	v_mov_b64_e32 v[28:29], v[2:3]
	v_mov_b64_e32 v[30:31], v[2:3]
	v_mov_b64_e32 v[32:33], v[2:3]
	v_mov_b64_e32 v[34:35], v[2:3]
	v_mov_b64_e32 v[36:37], v[2:3]
	v_mov_b64_e32 v[38:39], v[2:3]
	v_mov_b64_e32 v[40:41], v[2:3]
	v_mov_b64_e32 v[42:43], v[2:3]
	v_mov_b64_e32 v[44:45], v[2:3]
	v_mov_b64_e32 v[46:47], v[2:3]
	v_mov_b64_e32 v[48:49], v[2:3]
	v_mov_b64_e32 v[50:51], v[2:3]
	v_mov_b64_e32 v[52:53], v[2:3]
	v_mov_b64_e32 v[54:55], v[2:3]
	v_mov_b64_e32 v[56:57], v[2:3]
	v_mov_b64_e32 v[58:59], v[2:3]
	v_mov_b64_e32 v[60:61], v[2:3]
	v_mov_b64_e32 v[62:63], v[2:3]
	v_mov_b64_e32 v[64:65], v[2:3]
	v_mov_b64_e32 v[66:67], v[2:3]
	v_mov_b64_e32 v[68:69], v[2:3]
	v_mov_b64_e32 v[70:71], v[2:3]
	v_mov_b64_e32 v[72:73], v[2:3]
	v_mov_b64_e32 v[74:75], v[2:3]
	v_mov_b64_e32 v[76:77], v[2:3]
	v_mov_b64_e32 v[78:79], v[2:3]
	v_mov_b64_e32 v[80:81], v[2:3]
	v_mov_b64_e32 v[82:83], v[2:3]
	v_mov_b64_e32 v[84:85], v[2:3]
	v_mov_b64_e32 v[86:87], v[2:3]
	v_mov_b64_e32 v[88:89], v[2:3]
	v_mov_b64_e32 v[90:91], v[2:3]
	v_mov_b64_e32 v[92:93], v[2:3]
	v_mov_b64_e32 v[94:95], v[2:3]
	v_mov_b64_e32 v[96:97], v[2:3]
	v_mov_b64_e32 v[98:99], v[2:3]
	v_mov_b64_e32 v[100:101], v[2:3]
	v_mov_b64_e32 v[102:103], v[2:3]
	v_mov_b64_e32 v[104:105], v[2:3]
	v_mov_b64_e32 v[106:107], v[2:3]
	v_mov_b64_e32 v[108:109], v[2:3]
	v_mov_b64_e32 v[110:111], v[2:3]
	v_mov_b64_e32 v[112:113], v[2:3]
	v_mov_b64_e32 v[114:115], v[2:3]
	v_mov_b64_e32 v[116:117], v[2:3]
	v_mov_b64_e32 v[118:119], v[2:3]
	v_mov_b64_e32 v[120:121], v[2:3]
	v_mov_b64_e32 v[122:123], v[2:3]
	v_mov_b64_e32 v[124:125], v[2:3]
	v_mov_b64_e32 v[126:127], v[2:3]
	v_mov_b64_e32 v[128:129], v[2:3]

.LBB0_1367:
	s_ashr_i32 s27, s26, 31
	s_lshl_b64 s[28:29], s[26:27], 21
	s_add_u32 s28, s3, s28
	s_addc_u32 s29, s38, s29
	s_and_b64 s[36:37], s[8:9], exec
	s_cselect_b32 s11, s29, s35
	s_cselect_b32 s27, s28, s34
	s_add_u32 s69, s30, 0x100
	s_addc_u32 s70, s31, 0
	s_add_u32 s30, s34, 0x100080
	v_mov_b32_e32 v2, 0
	s_addc_u32 s31, s35, 0
	s_mov_b32 s71, -2
	v_mov_b32_e32 v3, 0
	v_mov_b64_e32 v[4:5], v[2:3]
	v_mov_b64_e32 v[6:7], v[2:3]
	v_mov_b64_e32 v[8:9], v[2:3]
	v_mov_b64_e32 v[10:11], v[2:3]
	v_mov_b64_e32 v[12:13], v[2:3]
	v_mov_b64_e32 v[14:15], v[2:3]
	v_mov_b64_e32 v[16:17], v[2:3]
	v_mov_b64_e32 v[18:19], v[2:3]
	v_mov_b64_e32 v[20:21], v[2:3]
	v_mov_b64_e32 v[22:23], v[2:3]
	v_mov_b64_e32 v[24:25], v[2:3]
	v_mov_b64_e32 v[26:27], v[2:3]
	v_mov_b64_e32 v[28:29], v[2:3]
	v_mov_b64_e32 v[30:31], v[2:3]
	v_mov_b64_e32 v[32:33], v[2:3]
	v_mov_b64_e32 v[34:35], v[2:3]
	v_mov_b64_e32 v[36:37], v[2:3]
	v_mov_b64_e32 v[38:39], v[2:3]
	v_mov_b64_e32 v[40:41], v[2:3]
	v_mov_b64_e32 v[42:43], v[2:3]
	v_mov_b64_e32 v[44:45], v[2:3]
	v_mov_b64_e32 v[46:47], v[2:3]
	v_mov_b64_e32 v[48:49], v[2:3]
	v_mov_b64_e32 v[50:51], v[2:3]
	v_mov_b64_e32 v[52:53], v[2:3]
	v_mov_b64_e32 v[54:55], v[2:3]
	v_mov_b64_e32 v[56:57], v[2:3]
	v_mov_b64_e32 v[58:59], v[2:3]
	v_mov_b64_e32 v[60:61], v[2:3]
	v_mov_b64_e32 v[62:63], v[2:3]
	v_mov_b64_e32 v[64:65], v[2:3]
	v_mov_b64_e32 v[66:67], v[2:3]
	v_mov_b64_e32 v[68:69], v[2:3]
	v_mov_b64_e32 v[70:71], v[2:3]
	v_mov_b64_e32 v[72:73], v[2:3]
	v_mov_b64_e32 v[74:75], v[2:3]
	v_mov_b64_e32 v[76:77], v[2:3]
	v_mov_b64_e32 v[78:79], v[2:3]
	v_mov_b64_e32 v[80:81], v[2:3]
	v_mov_b64_e32 v[82:83], v[2:3]
	v_mov_b64_e32 v[84:85], v[2:3]
	v_mov_b64_e32 v[86:87], v[2:3]
	v_mov_b64_e32 v[88:89], v[2:3]
	v_mov_b64_e32 v[90:91], v[2:3]
	v_mov_b64_e32 v[92:93], v[2:3]
	v_mov_b64_e32 v[94:95], v[2:3]
	v_mov_b64_e32 v[96:97], v[2:3]
	v_mov_b64_e32 v[98:99], v[2:3]
	v_mov_b64_e32 v[100:101], v[2:3]
	v_mov_b64_e32 v[102:103], v[2:3]
	v_mov_b64_e32 v[104:105], v[2:3]
	v_mov_b64_e32 v[106:107], v[2:3]
	v_mov_b64_e32 v[108:109], v[2:3]
	v_mov_b64_e32 v[110:111], v[2:3]
	v_mov_b64_e32 v[112:113], v[2:3]
	v_mov_b64_e32 v[114:115], v[2:3]
	v_mov_b64_e32 v[116:117], v[2:3]
	v_mov_b64_e32 v[118:119], v[2:3]
	v_mov_b64_e32 v[120:121], v[2:3]
	v_mov_b64_e32 v[122:123], v[2:3]
	v_mov_b64_e32 v[124:125], v[2:3]
	v_mov_b64_e32 v[126:127], v[2:3]
	v_mov_b64_e32 v[128:129], v[2:3]

.LBB0_1482:
	s_ashr_i32 s27, s26, 31
	s_lshl_b64 s[30:31], s[26:27], 19
	s_add_u32 s30, s3, s30
	s_addc_u32 s31, s42, s31
	s_and_b64 s[10:11], s[10:11], exec
	s_cselect_b32 s25, s31, s41
	s_cselect_b32 s27, s30, s40
	s_add_u32 s64, s38, 0x100
	s_addc_u32 s65, s39, 0
	s_add_u32 s10, s40, 0x40080
	v_mov_b32_e32 v2, 0
	s_addc_u32 s11, s41, 0
	s_mov_b32 s66, -2
	s_waitcnt lgkmcnt(0)
	v_mov_b32_e32 v3, 0
	v_mov_b64_e32 v[4:5], v[2:3]
	v_mov_b64_e32 v[6:7], v[2:3]
	v_mov_b64_e32 v[8:9], v[2:3]
	v_mov_b64_e32 v[10:11], v[2:3]
	v_mov_b64_e32 v[12:13], v[2:3]
	v_mov_b64_e32 v[14:15], v[2:3]
	v_mov_b64_e32 v[16:17], v[2:3]
	v_mov_b64_e32 v[18:19], v[2:3]
	v_mov_b64_e32 v[20:21], v[2:3]
	v_mov_b64_e32 v[22:23], v[2:3]
	v_mov_b64_e32 v[24:25], v[2:3]
	v_mov_b64_e32 v[26:27], v[2:3]
	v_mov_b64_e32 v[28:29], v[2:3]
	v_mov_b64_e32 v[30:31], v[2:3]
	v_mov_b64_e32 v[32:33], v[2:3]
	v_mov_b64_e32 v[34:35], v[2:3]
	v_mov_b64_e32 v[36:37], v[2:3]
	v_mov_b64_e32 v[38:39], v[2:3]
	v_mov_b64_e32 v[40:41], v[2:3]
	v_mov_b64_e32 v[42:43], v[2:3]
	v_mov_b64_e32 v[44:45], v[2:3]
	v_mov_b64_e32 v[46:47], v[2:3]
	v_mov_b64_e32 v[48:49], v[2:3]
	v_mov_b64_e32 v[50:51], v[2:3]
	v_mov_b64_e32 v[52:53], v[2:3]
	v_mov_b64_e32 v[54:55], v[2:3]
	v_mov_b64_e32 v[56:57], v[2:3]
	v_mov_b64_e32 v[58:59], v[2:3]
	v_mov_b64_e32 v[60:61], v[2:3]
	v_mov_b64_e32 v[62:63], v[2:3]
	v_mov_b64_e32 v[64:65], v[2:3]
	v_mov_b64_e32 v[66:67], v[2:3]
	v_mov_b64_e32 v[68:69], v[2:3]
	v_mov_b64_e32 v[70:71], v[2:3]
	v_mov_b64_e32 v[72:73], v[2:3]
	v_mov_b64_e32 v[74:75], v[2:3]
	v_mov_b64_e32 v[76:77], v[2:3]
	v_mov_b64_e32 v[78:79], v[2:3]
	v_mov_b64_e32 v[80:81], v[2:3]
	v_mov_b64_e32 v[82:83], v[2:3]
	v_mov_b64_e32 v[84:85], v[2:3]
	v_mov_b64_e32 v[86:87], v[2:3]
	v_mov_b64_e32 v[88:89], v[2:3]
	v_mov_b64_e32 v[90:91], v[2:3]
	v_mov_b64_e32 v[92:93], v[2:3]
	v_mov_b64_e32 v[94:95], v[2:3]
	v_mov_b64_e32 v[96:97], v[2:3]
	v_mov_b64_e32 v[98:99], v[2:3]
	v_mov_b64_e32 v[100:101], v[2:3]
	v_mov_b64_e32 v[102:103], v[2:3]
	v_mov_b64_e32 v[104:105], v[2:3]
	v_mov_b64_e32 v[106:107], v[2:3]
	v_mov_b64_e32 v[108:109], v[2:3]
	v_mov_b64_e32 v[110:111], v[2:3]
	v_mov_b64_e32 v[112:113], v[2:3]
	v_mov_b64_e32 v[114:115], v[2:3]
	v_mov_b64_e32 v[116:117], v[2:3]
	v_mov_b64_e32 v[118:119], v[2:3]
	v_mov_b64_e32 v[120:121], v[2:3]
	v_mov_b64_e32 v[122:123], v[2:3]
	v_mov_b64_e32 v[124:125], v[2:3]
	v_mov_b64_e32 v[126:127], v[2:3]
	v_mov_b64_e32 v[128:129], v[2:3]

.LBB0_1688:
	s_ashr_i32 s61, s60, 31
	s_lshl_b64 s[6:7], s[60:61], 21
	s_add_u32 s62, s18, s6
	s_addc_u32 s63, s19, s7
	s_and_b64 s[6:7], s[14:15], exec
	s_cselect_b32 s61, s63, s73
	s_cselect_b32 s67, s62, s72
	s_ashr_i32 s47, s46, 31
	s_lshl_b64 s[6:7], s[46:47], 21
	s_add_u32 s64, s11, s6
	s_addc_u32 s65, s26, s7
	s_and_b64 s[6:7], s[14:15], exec
	s_cselect_b32 s47, s65, s71
	s_cselect_b32 s69, s64, s70
	s_add_u32 s84, s70, 0x100
	s_addc_u32 s85, s71, 0
	s_add_u32 s70, s72, 0x100080
	v_mov_b32_e32 v2, 0
	s_addc_u32 s71, s73, 0
	s_mov_b32 s86, -2
	s_waitcnt lgkmcnt(0)
	v_mov_b32_e32 v3, 0
	v_mov_b64_e32 v[4:5], v[2:3]
	v_mov_b64_e32 v[6:7], v[2:3]
	v_mov_b64_e32 v[8:9], v[2:3]
	v_mov_b64_e32 v[10:11], v[2:3]
	v_mov_b64_e32 v[12:13], v[2:3]
	v_mov_b64_e32 v[14:15], v[2:3]
	v_mov_b64_e32 v[16:17], v[2:3]
	v_mov_b64_e32 v[18:19], v[2:3]
	v_mov_b64_e32 v[20:21], v[2:3]
	v_mov_b64_e32 v[22:23], v[2:3]
	v_mov_b64_e32 v[24:25], v[2:3]
	v_mov_b64_e32 v[26:27], v[2:3]
	v_mov_b64_e32 v[28:29], v[2:3]
	v_mov_b64_e32 v[30:31], v[2:3]
	v_mov_b64_e32 v[32:33], v[2:3]
	v_mov_b64_e32 v[34:35], v[2:3]
	v_mov_b64_e32 v[36:37], v[2:3]
	v_mov_b64_e32 v[38:39], v[2:3]
	v_mov_b64_e32 v[40:41], v[2:3]
	v_mov_b64_e32 v[42:43], v[2:3]
	v_mov_b64_e32 v[44:45], v[2:3]
	v_mov_b64_e32 v[46:47], v[2:3]
	v_mov_b64_e32 v[48:49], v[2:3]
	v_mov_b64_e32 v[50:51], v[2:3]
	v_mov_b64_e32 v[52:53], v[2:3]
	v_mov_b64_e32 v[54:55], v[2:3]
	v_mov_b64_e32 v[56:57], v[2:3]
	v_mov_b64_e32 v[58:59], v[2:3]
	v_mov_b64_e32 v[60:61], v[2:3]
	v_mov_b64_e32 v[62:63], v[2:3]
	v_mov_b64_e32 v[64:65], v[2:3]
	v_mov_b64_e32 v[66:67], v[2:3]
	v_mov_b64_e32 v[68:69], v[2:3]
	v_mov_b64_e32 v[70:71], v[2:3]
	v_mov_b64_e32 v[72:73], v[2:3]
	v_mov_b64_e32 v[74:75], v[2:3]
	v_mov_b64_e32 v[76:77], v[2:3]
	v_mov_b64_e32 v[78:79], v[2:3]
	v_mov_b64_e32 v[80:81], v[2:3]
	v_mov_b64_e32 v[82:83], v[2:3]
	v_mov_b64_e32 v[84:85], v[2:3]
	v_mov_b64_e32 v[86:87], v[2:3]
	v_mov_b64_e32 v[88:89], v[2:3]
	v_mov_b64_e32 v[90:91], v[2:3]
	v_mov_b64_e32 v[92:93], v[2:3]
	v_mov_b64_e32 v[94:95], v[2:3]
	v_mov_b64_e32 v[96:97], v[2:3]
	v_mov_b64_e32 v[98:99], v[2:3]
	v_mov_b64_e32 v[100:101], v[2:3]
	v_mov_b64_e32 v[102:103], v[2:3]
	v_mov_b64_e32 v[104:105], v[2:3]
	v_mov_b64_e32 v[106:107], v[2:3]
	v_mov_b64_e32 v[108:109], v[2:3]
	v_mov_b64_e32 v[110:111], v[2:3]
	v_mov_b64_e32 v[112:113], v[2:3]
	v_mov_b64_e32 v[114:115], v[2:3]
	v_mov_b64_e32 v[116:117], v[2:3]
	v_mov_b64_e32 v[118:119], v[2:3]
	v_mov_b64_e32 v[120:121], v[2:3]
	v_mov_b64_e32 v[122:123], v[2:3]
	v_mov_b64_e32 v[124:125], v[2:3]
	v_mov_b64_e32 v[126:127], v[2:3]
	v_mov_b64_e32 v[128:129], v[2:3]

.LBB0_1770:
	s_ashr_i32 s73, s72, 31
	s_lshl_b64 s[6:7], s[72:73], 20
	s_add_u32 s74, s58, s6
	s_addc_u32 s75, s59, s7
	s_and_b64 s[6:7], s[68:69], exec
	s_cselect_b32 s26, s75, s9
	s_cselect_b32 s27, s74, s8
	s_ashr_i32 s71, s70, 31
	s_lshl_b64 s[6:7], s[70:71], 20
	s_add_u32 s76, s15, s6
	s_addc_u32 s77, s39, s7
	s_and_b64 s[6:7], s[68:69], exec
	s_cselect_b32 s28, s77, s79
	s_cselect_b32 s29, s76, s78
	s_add_u32 s8, s8, 0x80080
	s_addc_u32 s9, s9, 0
	s_add_u32 s40, s78, 0x100
	v_mov_b32_e32 v2, 0
	s_addc_u32 s41, s79, 0
	s_mov_b32 s71, -2
	v_mov_b32_e32 v3, 0
	v_mov_b64_e32 v[4:5], v[2:3]
	v_mov_b64_e32 v[6:7], v[2:3]
	v_mov_b64_e32 v[8:9], v[2:3]
	v_mov_b64_e32 v[10:11], v[2:3]
	v_mov_b64_e32 v[12:13], v[2:3]
	v_mov_b64_e32 v[14:15], v[2:3]
	v_mov_b64_e32 v[16:17], v[2:3]
	v_mov_b64_e32 v[18:19], v[2:3]
	v_mov_b64_e32 v[20:21], v[2:3]
	v_mov_b64_e32 v[22:23], v[2:3]
	v_mov_b64_e32 v[24:25], v[2:3]
	v_mov_b64_e32 v[26:27], v[2:3]
	v_mov_b64_e32 v[28:29], v[2:3]
	v_mov_b64_e32 v[30:31], v[2:3]
	v_mov_b64_e32 v[32:33], v[2:3]
	v_mov_b64_e32 v[34:35], v[2:3]
	v_mov_b64_e32 v[36:37], v[2:3]
	v_mov_b64_e32 v[38:39], v[2:3]
	v_mov_b64_e32 v[40:41], v[2:3]
	v_mov_b64_e32 v[42:43], v[2:3]
	v_mov_b64_e32 v[44:45], v[2:3]
	v_mov_b64_e32 v[46:47], v[2:3]
	v_mov_b64_e32 v[48:49], v[2:3]
	v_mov_b64_e32 v[50:51], v[2:3]
	v_mov_b64_e32 v[52:53], v[2:3]
	v_mov_b64_e32 v[54:55], v[2:3]
	v_mov_b64_e32 v[56:57], v[2:3]
	v_mov_b64_e32 v[58:59], v[2:3]
	v_mov_b64_e32 v[60:61], v[2:3]
	v_mov_b64_e32 v[62:63], v[2:3]
	v_mov_b64_e32 v[64:65], v[2:3]
	v_mov_b64_e32 v[66:67], v[2:3]
	v_mov_b64_e32 v[68:69], v[2:3]
	v_mov_b64_e32 v[70:71], v[2:3]
	v_mov_b64_e32 v[72:73], v[2:3]
	v_mov_b64_e32 v[74:75], v[2:3]
	v_mov_b64_e32 v[76:77], v[2:3]
	v_mov_b64_e32 v[78:79], v[2:3]
	v_mov_b64_e32 v[80:81], v[2:3]
	v_mov_b64_e32 v[82:83], v[2:3]
	v_mov_b64_e32 v[84:85], v[2:3]
	v_mov_b64_e32 v[86:87], v[2:3]
	v_mov_b64_e32 v[88:89], v[2:3]
	v_mov_b64_e32 v[90:91], v[2:3]
	v_mov_b64_e32 v[92:93], v[2:3]
	v_mov_b64_e32 v[94:95], v[2:3]
	v_mov_b64_e32 v[96:97], v[2:3]
	v_mov_b64_e32 v[98:99], v[2:3]
	v_mov_b64_e32 v[100:101], v[2:3]
	v_mov_b64_e32 v[102:103], v[2:3]
	v_mov_b64_e32 v[104:105], v[2:3]
	v_mov_b64_e32 v[106:107], v[2:3]
	v_mov_b64_e32 v[108:109], v[2:3]
	v_mov_b64_e32 v[110:111], v[2:3]
	v_mov_b64_e32 v[112:113], v[2:3]
	v_mov_b64_e32 v[114:115], v[2:3]
	v_mov_b64_e32 v[116:117], v[2:3]
	v_mov_b64_e32 v[118:119], v[2:3]
	v_mov_b64_e32 v[120:121], v[2:3]
	v_mov_b64_e32 v[122:123], v[2:3]
	v_mov_b64_e32 v[124:125], v[2:3]
	v_mov_b64_e32 v[126:127], v[2:3]
	v_mov_b64_e32 v[128:129], v[2:3]

.LBB0_1922:
	v_mov_b32_e32 v2, 0
	s_mov_b32 s65, 0
	s_mov_b64 s[10:11], -1
	s_mov_b64 s[78:79], 0
	v_mov_b32_e32 v3, 0
	v_mov_b64_e32 v[4:5], v[2:3]
	v_mov_b64_e32 v[6:7], v[2:3]
	v_mov_b64_e32 v[8:9], v[2:3]
	v_mov_b64_e32 v[10:11], v[2:3]
	v_mov_b64_e32 v[12:13], v[2:3]
	v_mov_b64_e32 v[14:15], v[2:3]
	v_mov_b64_e32 v[16:17], v[2:3]
	v_mov_b64_e32 v[18:19], v[2:3]
	v_mov_b64_e32 v[20:21], v[2:3]
	v_mov_b64_e32 v[22:23], v[2:3]
	v_mov_b64_e32 v[24:25], v[2:3]
	v_mov_b64_e32 v[26:27], v[2:3]
	v_mov_b64_e32 v[28:29], v[2:3]
	v_mov_b64_e32 v[30:31], v[2:3]
	v_mov_b64_e32 v[32:33], v[2:3]
	v_mov_b64_e32 v[34:35], v[2:3]
	v_mov_b64_e32 v[36:37], v[2:3]
	v_mov_b64_e32 v[38:39], v[2:3]
	v_mov_b64_e32 v[40:41], v[2:3]
	v_mov_b64_e32 v[42:43], v[2:3]
	v_mov_b64_e32 v[44:45], v[2:3]
	v_mov_b64_e32 v[46:47], v[2:3]
	v_mov_b64_e32 v[48:49], v[2:3]
	v_mov_b64_e32 v[50:51], v[2:3]
	v_mov_b64_e32 v[52:53], v[2:3]
	v_mov_b64_e32 v[54:55], v[2:3]
	v_mov_b64_e32 v[56:57], v[2:3]
	v_mov_b64_e32 v[58:59], v[2:3]
	v_mov_b64_e32 v[60:61], v[2:3]
	v_mov_b64_e32 v[62:63], v[2:3]
	v_mov_b64_e32 v[64:65], v[2:3]
	v_mov_b64_e32 v[66:67], v[2:3]
	v_mov_b64_e32 v[68:69], v[2:3]
	v_mov_b64_e32 v[70:71], v[2:3]
	v_mov_b64_e32 v[72:73], v[2:3]
	v_mov_b64_e32 v[74:75], v[2:3]
	v_mov_b64_e32 v[76:77], v[2:3]
	v_mov_b64_e32 v[78:79], v[2:3]
	v_mov_b64_e32 v[80:81], v[2:3]
	v_mov_b64_e32 v[82:83], v[2:3]
	v_mov_b64_e32 v[84:85], v[2:3]
	v_mov_b64_e32 v[86:87], v[2:3]
	v_mov_b64_e32 v[88:89], v[2:3]
	v_mov_b64_e32 v[90:91], v[2:3]
	v_mov_b64_e32 v[92:93], v[2:3]
	v_mov_b64_e32 v[94:95], v[2:3]
	v_mov_b64_e32 v[96:97], v[2:3]
	v_mov_b64_e32 v[98:99], v[2:3]
	v_mov_b64_e32 v[100:101], v[2:3]
	v_mov_b64_e32 v[102:103], v[2:3]
	v_mov_b64_e32 v[104:105], v[2:3]
	v_mov_b64_e32 v[106:107], v[2:3]
	v_mov_b64_e32 v[108:109], v[2:3]
	v_mov_b64_e32 v[110:111], v[2:3]
	v_mov_b64_e32 v[112:113], v[2:3]
	v_mov_b64_e32 v[114:115], v[2:3]
	v_mov_b64_e32 v[116:117], v[2:3]
	v_mov_b64_e32 v[118:119], v[2:3]
	v_mov_b64_e32 v[120:121], v[2:3]
	v_mov_b64_e32 v[122:123], v[2:3]
	v_mov_b64_e32 v[124:125], v[2:3]
	v_mov_b64_e32 v[126:127], v[2:3]
	v_mov_b64_e32 v[128:129], v[2:3]

.LBB0_1983:
	s_ashr_i32 s63, s62, 31
	s_lshl_b64 s[6:7], s[62:63], 21
	s_add_u32 s64, s18, s6
	s_addc_u32 s65, s19, s7
	s_and_b64 s[6:7], s[46:47], exec
	s_cselect_b32 s63, s65, s75
	s_cselect_b32 s69, s64, s74
	s_ashr_i32 s61, s60, 31
	s_lshl_b64 s[6:7], s[60:61], 21
	s_add_u32 s66, s15, s6
	s_addc_u32 s67, s39, s7
	s_and_b64 s[6:7], s[46:47], exec
	s_cselect_b32 s61, s67, s73
	s_cselect_b32 s80, s66, s72
	s_add_u32 s81, s72, 0x100
	s_addc_u32 s82, s73, 0
	s_add_u32 s72, s74, 0x100080
	v_mov_b32_e32 v2, 0
	s_addc_u32 s73, s75, 0
	s_mov_b32 s83, -2
	s_waitcnt lgkmcnt(0)
	v_mov_b32_e32 v3, 0
	v_mov_b64_e32 v[4:5], v[2:3]
	v_mov_b64_e32 v[6:7], v[2:3]
	v_mov_b64_e32 v[8:9], v[2:3]
	v_mov_b64_e32 v[10:11], v[2:3]
	v_mov_b64_e32 v[12:13], v[2:3]
	v_mov_b64_e32 v[14:15], v[2:3]
	v_mov_b64_e32 v[16:17], v[2:3]
	v_mov_b64_e32 v[18:19], v[2:3]
	v_mov_b64_e32 v[20:21], v[2:3]
	v_mov_b64_e32 v[22:23], v[2:3]
	v_mov_b64_e32 v[24:25], v[2:3]
	v_mov_b64_e32 v[26:27], v[2:3]
	v_mov_b64_e32 v[28:29], v[2:3]
	v_mov_b64_e32 v[30:31], v[2:3]
	v_mov_b64_e32 v[32:33], v[2:3]
	v_mov_b64_e32 v[34:35], v[2:3]
	v_mov_b64_e32 v[36:37], v[2:3]
	v_mov_b64_e32 v[38:39], v[2:3]
	v_mov_b64_e32 v[40:41], v[2:3]
	v_mov_b64_e32 v[42:43], v[2:3]
	v_mov_b64_e32 v[44:45], v[2:3]
	v_mov_b64_e32 v[46:47], v[2:3]
	v_mov_b64_e32 v[48:49], v[2:3]
	v_mov_b64_e32 v[50:51], v[2:3]
	v_mov_b64_e32 v[52:53], v[2:3]
	v_mov_b64_e32 v[54:55], v[2:3]
	v_mov_b64_e32 v[56:57], v[2:3]
	v_mov_b64_e32 v[58:59], v[2:3]
	v_mov_b64_e32 v[60:61], v[2:3]
	v_mov_b64_e32 v[62:63], v[2:3]
	v_mov_b64_e32 v[64:65], v[2:3]
	v_mov_b64_e32 v[66:67], v[2:3]
	v_mov_b64_e32 v[68:69], v[2:3]
	v_mov_b64_e32 v[70:71], v[2:3]
	v_mov_b64_e32 v[72:73], v[2:3]
	v_mov_b64_e32 v[74:75], v[2:3]
	v_mov_b64_e32 v[76:77], v[2:3]
	v_mov_b64_e32 v[78:79], v[2:3]
	v_mov_b64_e32 v[80:81], v[2:3]
	v_mov_b64_e32 v[82:83], v[2:3]
	v_mov_b64_e32 v[84:85], v[2:3]
	v_mov_b64_e32 v[86:87], v[2:3]
	v_mov_b64_e32 v[88:89], v[2:3]
	v_mov_b64_e32 v[90:91], v[2:3]
	v_mov_b64_e32 v[92:93], v[2:3]
	v_mov_b64_e32 v[94:95], v[2:3]
	v_mov_b64_e32 v[96:97], v[2:3]
	v_mov_b64_e32 v[98:99], v[2:3]
	v_mov_b64_e32 v[100:101], v[2:3]
	v_mov_b64_e32 v[102:103], v[2:3]
	v_mov_b64_e32 v[104:105], v[2:3]
	v_mov_b64_e32 v[106:107], v[2:3]
	v_mov_b64_e32 v[108:109], v[2:3]
	v_mov_b64_e32 v[110:111], v[2:3]
	v_mov_b64_e32 v[112:113], v[2:3]
	v_mov_b64_e32 v[114:115], v[2:3]
	v_mov_b64_e32 v[116:117], v[2:3]
	v_mov_b64_e32 v[118:119], v[2:3]
	v_mov_b64_e32 v[120:121], v[2:3]
	v_mov_b64_e32 v[122:123], v[2:3]
	v_mov_b64_e32 v[124:125], v[2:3]
	v_mov_b64_e32 v[126:127], v[2:3]
	v_mov_b64_e32 v[128:129], v[2:3]

.LBB0_2066:
	s_ashr_i32 s67, s66, 31
	s_lshl_b64 s[6:7], s[66:67], 20
	s_add_u32 s68, s18, s6
	s_addc_u32 s69, s19, s7
	s_and_b64 s[6:7], s[8:9], exec
	s_cselect_b32 s28, s69, s13
	s_cselect_b32 s29, s68, s12
	s_ashr_i32 s65, s64, 31
	s_lshl_b64 s[6:7], s[64:65], 20
	s_add_u32 s70, s56, s6
	s_addc_u32 s71, s57, s7
	s_and_b64 s[6:7], s[8:9], exec
	s_cselect_b32 s65, s71, s11
	s_cselect_b32 s67, s70, s10
	s_add_u32 s83, s10, 0x100
	s_addc_u32 s84, s11, 0
	s_add_u32 s10, s12, 0x80080
	v_mov_b32_e32 v10, 0
	s_addc_u32 s11, s13, 0
	s_mov_b32 s85, -2
	v_mov_b32_e32 v11, 0
	v_mov_b64_e32 v[12:13], v[10:11]
	v_mov_b64_e32 v[14:15], v[10:11]
	v_mov_b64_e32 v[16:17], v[10:11]
	v_mov_b64_e32 v[18:19], v[10:11]
	v_mov_b64_e32 v[20:21], v[10:11]
	v_mov_b64_e32 v[22:23], v[10:11]
	v_mov_b64_e32 v[24:25], v[10:11]
	v_mov_b64_e32 v[26:27], v[10:11]
	v_mov_b64_e32 v[28:29], v[10:11]
	v_mov_b64_e32 v[30:31], v[10:11]
	v_mov_b64_e32 v[32:33], v[10:11]
	v_mov_b64_e32 v[34:35], v[10:11]
	v_mov_b64_e32 v[36:37], v[10:11]
	v_mov_b64_e32 v[38:39], v[10:11]
	v_mov_b64_e32 v[40:41], v[10:11]
	v_mov_b64_e32 v[42:43], v[10:11]
	v_mov_b64_e32 v[44:45], v[10:11]
	v_mov_b64_e32 v[46:47], v[10:11]
	v_mov_b64_e32 v[48:49], v[10:11]
	v_mov_b64_e32 v[50:51], v[10:11]
	v_mov_b64_e32 v[52:53], v[10:11]
	v_mov_b64_e32 v[54:55], v[10:11]
	v_mov_b64_e32 v[56:57], v[10:11]
	v_mov_b64_e32 v[58:59], v[10:11]
	v_mov_b64_e32 v[60:61], v[10:11]
	v_mov_b64_e32 v[62:63], v[10:11]
	v_mov_b64_e32 v[64:65], v[10:11]
	v_mov_b64_e32 v[66:67], v[10:11]
	v_mov_b64_e32 v[68:69], v[10:11]
	v_mov_b64_e32 v[70:71], v[10:11]
	v_mov_b64_e32 v[72:73], v[10:11]
	v_mov_b64_e32 v[74:75], v[10:11]
	v_mov_b64_e32 v[76:77], v[10:11]
	v_mov_b64_e32 v[78:79], v[10:11]
	v_mov_b64_e32 v[80:81], v[10:11]
	v_mov_b64_e32 v[82:83], v[10:11]
	v_mov_b64_e32 v[84:85], v[10:11]
	v_mov_b64_e32 v[86:87], v[10:11]
	v_mov_b64_e32 v[88:89], v[10:11]
	v_mov_b64_e32 v[90:91], v[10:11]
	v_mov_b64_e32 v[92:93], v[10:11]
	v_mov_b64_e32 v[94:95], v[10:11]
	v_mov_b64_e32 v[96:97], v[10:11]
	v_mov_b64_e32 v[98:99], v[10:11]
	v_mov_b64_e32 v[100:101], v[10:11]
	v_mov_b64_e32 v[102:103], v[10:11]
	v_mov_b64_e32 v[104:105], v[10:11]
	v_mov_b64_e32 v[106:107], v[10:11]
	v_mov_b64_e32 v[108:109], v[10:11]
	v_mov_b64_e32 v[110:111], v[10:11]
	v_mov_b64_e32 v[112:113], v[10:11]
	v_mov_b64_e32 v[114:115], v[10:11]
	v_mov_b64_e32 v[116:117], v[10:11]
	v_mov_b64_e32 v[118:119], v[10:11]
	v_mov_b64_e32 v[120:121], v[10:11]
	v_mov_b64_e32 v[122:123], v[10:11]
	v_mov_b64_e32 v[124:125], v[10:11]
	v_mov_b64_e32 v[126:127], v[10:11]
	v_mov_b64_e32 v[128:129], v[10:11]
	v_mov_b64_e32 v[130:131], v[10:11]
	v_mov_b64_e32 v[132:133], v[10:11]
	v_mov_b64_e32 v[134:135], v[10:11]
	v_mov_b64_e32 v[136:137], v[10:11]

.LBB0_2117:
	s_add_u32 s69, s40, 0x100
	s_addc_u32 s70, s41, 0
	s_add_u32 s40, s42, 0x2b0080
	v_mov_b32_e32 v2, 0
	s_addc_u32 s41, s43, 0
	s_mov_b32 s71, -2
	s_waitcnt lgkmcnt(0)
	v_mov_b32_e32 v3, 0
	v_mov_b64_e32 v[4:5], v[2:3]
	v_mov_b64_e32 v[6:7], v[2:3]
	v_mov_b64_e32 v[8:9], v[2:3]
	v_mov_b64_e32 v[10:11], v[2:3]
	v_mov_b64_e32 v[12:13], v[2:3]
	v_mov_b64_e32 v[14:15], v[2:3]
	v_mov_b64_e32 v[16:17], v[2:3]
	v_mov_b64_e32 v[18:19], v[2:3]
	v_mov_b64_e32 v[20:21], v[2:3]
	v_mov_b64_e32 v[22:23], v[2:3]
	v_mov_b64_e32 v[24:25], v[2:3]
	v_mov_b64_e32 v[26:27], v[2:3]
	v_mov_b64_e32 v[28:29], v[2:3]
	v_mov_b64_e32 v[30:31], v[2:3]
	v_mov_b64_e32 v[32:33], v[2:3]
	v_mov_b64_e32 v[34:35], v[2:3]
	v_mov_b64_e32 v[36:37], v[2:3]
	v_mov_b64_e32 v[38:39], v[2:3]
	v_mov_b64_e32 v[40:41], v[2:3]
	v_mov_b64_e32 v[42:43], v[2:3]
	v_mov_b64_e32 v[44:45], v[2:3]
	v_mov_b64_e32 v[46:47], v[2:3]
	v_mov_b64_e32 v[48:49], v[2:3]
	v_mov_b64_e32 v[50:51], v[2:3]
	v_mov_b64_e32 v[52:53], v[2:3]
	v_mov_b64_e32 v[54:55], v[2:3]
	v_mov_b64_e32 v[56:57], v[2:3]
	v_mov_b64_e32 v[58:59], v[2:3]
	v_mov_b64_e32 v[60:61], v[2:3]
	v_mov_b64_e32 v[62:63], v[2:3]
	v_mov_b64_e32 v[64:65], v[2:3]
	v_mov_b64_e32 v[66:67], v[2:3]
	v_mov_b64_e32 v[68:69], v[2:3]
	v_mov_b64_e32 v[70:71], v[2:3]
	v_mov_b64_e32 v[72:73], v[2:3]
	v_mov_b64_e32 v[74:75], v[2:3]
	v_mov_b64_e32 v[76:77], v[2:3]
	v_mov_b64_e32 v[78:79], v[2:3]
	v_mov_b64_e32 v[80:81], v[2:3]
	v_mov_b64_e32 v[82:83], v[2:3]
	v_mov_b64_e32 v[84:85], v[2:3]
	v_mov_b64_e32 v[86:87], v[2:3]
	v_mov_b64_e32 v[88:89], v[2:3]
	v_mov_b64_e32 v[90:91], v[2:3]
	v_mov_b64_e32 v[92:93], v[2:3]
	v_mov_b64_e32 v[94:95], v[2:3]
	v_mov_b64_e32 v[96:97], v[2:3]
	v_mov_b64_e32 v[98:99], v[2:3]
	v_mov_b64_e32 v[100:101], v[2:3]
	v_mov_b64_e32 v[102:103], v[2:3]
	v_mov_b64_e32 v[104:105], v[2:3]
	v_mov_b64_e32 v[106:107], v[2:3]
	v_mov_b64_e32 v[108:109], v[2:3]
	v_mov_b64_e32 v[110:111], v[2:3]
	v_mov_b64_e32 v[112:113], v[2:3]
	v_mov_b64_e32 v[114:115], v[2:3]
	v_mov_b64_e32 v[116:117], v[2:3]
	v_mov_b64_e32 v[118:119], v[2:3]
	v_mov_b64_e32 v[120:121], v[2:3]
	v_mov_b64_e32 v[122:123], v[2:3]
	v_mov_b64_e32 v[124:125], v[2:3]
	v_mov_b64_e32 v[126:127], v[2:3]
	v_mov_b64_e32 v[128:129], v[2:3]

.LBB0_2158:
	s_ashr_i32 s41, s40, 31
	s_lshl_b64 s[12:13], s[40:41], 20
	s_add_u32 s44, s18, s12
	s_addc_u32 s45, s19, s13
	s_and_b64 s[12:13], s[42:43], exec
	s_cselect_b32 s41, s45, s11
	s_cselect_b32 s75, s44, s10
	s_ashr_i32 s39, s38, 31
	s_lshl_b64 s[12:13], s[38:39], 20
	s_add_u32 s46, s3, s12
	s_addc_u32 s47, s49, s13
	s_and_b64 s[12:13], s[42:43], exec
	s_cselect_b32 s39, s47, s9
	s_cselect_b32 s76, s46, s8
	s_add_u32 s77, s8, 0x100
	s_addc_u32 s78, s9, 0
	s_add_u32 s8, s10, 0x80080
	v_mov_b32_e32 v10, 0
	s_addc_u32 s9, s11, 0
	s_mov_b32 s79, -2
	v_mov_b32_e32 v11, 0
	v_mov_b64_e32 v[12:13], v[10:11]
	v_mov_b64_e32 v[14:15], v[10:11]
	v_mov_b64_e32 v[16:17], v[10:11]
	v_mov_b64_e32 v[18:19], v[10:11]
	v_mov_b64_e32 v[20:21], v[10:11]
	v_mov_b64_e32 v[22:23], v[10:11]
	v_mov_b64_e32 v[24:25], v[10:11]
	v_mov_b64_e32 v[26:27], v[10:11]
	v_mov_b64_e32 v[28:29], v[10:11]
	v_mov_b64_e32 v[30:31], v[10:11]
	v_mov_b64_e32 v[32:33], v[10:11]
	v_mov_b64_e32 v[34:35], v[10:11]
	v_mov_b64_e32 v[36:37], v[10:11]
	v_mov_b64_e32 v[38:39], v[10:11]
	v_mov_b64_e32 v[40:41], v[10:11]
	v_mov_b64_e32 v[42:43], v[10:11]
	v_mov_b64_e32 v[44:45], v[10:11]
	v_mov_b64_e32 v[46:47], v[10:11]
	v_mov_b64_e32 v[48:49], v[10:11]
	v_mov_b64_e32 v[50:51], v[10:11]
	v_mov_b64_e32 v[52:53], v[10:11]
	v_mov_b64_e32 v[54:55], v[10:11]
	v_mov_b64_e32 v[56:57], v[10:11]
	v_mov_b64_e32 v[58:59], v[10:11]
	v_mov_b64_e32 v[60:61], v[10:11]
	v_mov_b64_e32 v[62:63], v[10:11]
	v_mov_b64_e32 v[64:65], v[10:11]
	v_mov_b64_e32 v[66:67], v[10:11]
	v_mov_b64_e32 v[68:69], v[10:11]
	v_mov_b64_e32 v[70:71], v[10:11]
	v_mov_b64_e32 v[72:73], v[10:11]
	v_mov_b64_e32 v[74:75], v[10:11]
	v_mov_b64_e32 v[76:77], v[10:11]
	v_mov_b64_e32 v[78:79], v[10:11]
	v_mov_b64_e32 v[80:81], v[10:11]
	v_mov_b64_e32 v[82:83], v[10:11]
	v_mov_b64_e32 v[84:85], v[10:11]
	v_mov_b64_e32 v[86:87], v[10:11]
	v_mov_b64_e32 v[88:89], v[10:11]
	v_mov_b64_e32 v[90:91], v[10:11]
	v_mov_b64_e32 v[92:93], v[10:11]
	v_mov_b64_e32 v[94:95], v[10:11]
	v_mov_b64_e32 v[96:97], v[10:11]
	v_mov_b64_e32 v[98:99], v[10:11]
	v_mov_b64_e32 v[100:101], v[10:11]
	v_mov_b64_e32 v[102:103], v[10:11]
	v_mov_b64_e32 v[104:105], v[10:11]
	v_mov_b64_e32 v[106:107], v[10:11]
	v_mov_b64_e32 v[108:109], v[10:11]
	v_mov_b64_e32 v[110:111], v[10:11]
	v_mov_b64_e32 v[112:113], v[10:11]
	v_mov_b64_e32 v[114:115], v[10:11]
	v_mov_b64_e32 v[116:117], v[10:11]
	v_mov_b64_e32 v[118:119], v[10:11]
	v_mov_b64_e32 v[120:121], v[10:11]
	v_mov_b64_e32 v[122:123], v[10:11]
	v_mov_b64_e32 v[124:125], v[10:11]
	v_mov_b64_e32 v[126:127], v[10:11]
	v_mov_b64_e32 v[128:129], v[10:11]
	v_mov_b64_e32 v[130:131], v[10:11]
	v_mov_b64_e32 v[132:133], v[10:11]
	v_mov_b64_e32 v[134:135], v[10:11]
	v_mov_b64_e32 v[136:137], v[10:11]

.LBB0_2247:
	s_add_u32 s62, s26, 0x100
	s_addc_u32 s63, s27, 0
	s_add_u32 s26, s28, 0x2b0080
	v_mov_b32_e32 v2, 0
	s_addc_u32 s27, s29, 0
	s_mov_b32 s64, -2
	s_waitcnt lgkmcnt(0)
	v_mov_b32_e32 v3, 0
	v_mov_b64_e32 v[4:5], v[2:3]
	v_mov_b64_e32 v[6:7], v[2:3]
	v_mov_b64_e32 v[8:9], v[2:3]
	v_mov_b64_e32 v[10:11], v[2:3]
	v_mov_b64_e32 v[12:13], v[2:3]
	v_mov_b64_e32 v[14:15], v[2:3]
	v_mov_b64_e32 v[16:17], v[2:3]
	v_mov_b64_e32 v[18:19], v[2:3]
	v_mov_b64_e32 v[20:21], v[2:3]
	v_mov_b64_e32 v[22:23], v[2:3]
	v_mov_b64_e32 v[24:25], v[2:3]
	v_mov_b64_e32 v[26:27], v[2:3]
	v_mov_b64_e32 v[28:29], v[2:3]
	v_mov_b64_e32 v[30:31], v[2:3]
	v_mov_b64_e32 v[32:33], v[2:3]
	v_mov_b64_e32 v[34:35], v[2:3]
	v_mov_b64_e32 v[36:37], v[2:3]
	v_mov_b64_e32 v[38:39], v[2:3]
	v_mov_b64_e32 v[40:41], v[2:3]
	v_mov_b64_e32 v[42:43], v[2:3]
	v_mov_b64_e32 v[44:45], v[2:3]
	v_mov_b64_e32 v[46:47], v[2:3]
	v_mov_b64_e32 v[48:49], v[2:3]
	v_mov_b64_e32 v[50:51], v[2:3]
	v_mov_b64_e32 v[52:53], v[2:3]
	v_mov_b64_e32 v[54:55], v[2:3]
	v_mov_b64_e32 v[56:57], v[2:3]
	v_mov_b64_e32 v[58:59], v[2:3]
	v_mov_b64_e32 v[60:61], v[2:3]
	v_mov_b64_e32 v[62:63], v[2:3]
	v_mov_b64_e32 v[64:65], v[2:3]
	v_mov_b64_e32 v[66:67], v[2:3]
	v_mov_b64_e32 v[68:69], v[2:3]
	v_mov_b64_e32 v[70:71], v[2:3]
	v_mov_b64_e32 v[72:73], v[2:3]
	v_mov_b64_e32 v[74:75], v[2:3]
	v_mov_b64_e32 v[76:77], v[2:3]
	v_mov_b64_e32 v[78:79], v[2:3]
	v_mov_b64_e32 v[80:81], v[2:3]
	v_mov_b64_e32 v[82:83], v[2:3]
	v_mov_b64_e32 v[84:85], v[2:3]
	v_mov_b64_e32 v[86:87], v[2:3]
	v_mov_b64_e32 v[88:89], v[2:3]
	v_mov_b64_e32 v[90:91], v[2:3]
	v_mov_b64_e32 v[92:93], v[2:3]
	v_mov_b64_e32 v[94:95], v[2:3]
	v_mov_b64_e32 v[96:97], v[2:3]
	v_mov_b64_e32 v[98:99], v[2:3]
	v_mov_b64_e32 v[100:101], v[2:3]
	v_mov_b64_e32 v[102:103], v[2:3]
	v_mov_b64_e32 v[104:105], v[2:3]
	v_mov_b64_e32 v[106:107], v[2:3]
	v_mov_b64_e32 v[108:109], v[2:3]
	v_mov_b64_e32 v[110:111], v[2:3]
	v_mov_b64_e32 v[112:113], v[2:3]
	v_mov_b64_e32 v[114:115], v[2:3]
	v_mov_b64_e32 v[116:117], v[2:3]
	v_mov_b64_e32 v[118:119], v[2:3]
	v_mov_b64_e32 v[120:121], v[2:3]
	v_mov_b64_e32 v[122:123], v[2:3]
	v_mov_b64_e32 v[124:125], v[2:3]
	v_mov_b64_e32 v[126:127], v[2:3]
	v_mov_b64_e32 v[128:129], v[2:3]
